# b_w_out transposes moved from after the A-out unit into the B-in tail (with the gate folding); only w_v is left after the A-out unit
# baseline (speedup 1.0000x reference)
.LBB0_354:
	s_mov_b32 s98, 1
	s_mov_b32 s70, 0x2c00
	s_mov_b32 s71, 0x3400
	s_mov_b32 s72, 0x800
	s_mov_b32 s73, 0x0
	s_mov_b32 s74, 0x0
	s_mov_b32 s75, 0x33ff
	s_lshl_b32 s76, s70, 5
	s_lshl_b32 s77, s70, 7
	s_lshl_b32 s78, s70, 6
	s_lshl_b32 s79, s70, 1
	s_branch .Lp0_entry

.LBB0_540:
	s_cmp_lt_u32 s2, 0x40
	s_cbranch_scc1 .Lp4_resume
	s_mov_b32 s98, 2
	s_mov_b32 s70, 0x3200
	s_mov_b32 s71, 0x3800
	s_mov_b32 s72, 0x600
	s_mov_b32 s73, 0x3400
	s_mov_b32 s74, 0x1000
	s_mov_b32 s75, 0x37ff
	s_lshl_b32 s76, s70, 5
	s_lshl_b32 s77, s70, 7
	s_lshl_b32 s78, s70, 6
	s_lshl_b32 s79, s70, 1
	s_branch .Lp0_entry
